# P7 stage_rs: unit ssq rows via LDS-DMA at unit start instead of global loads in the epilogue
# speedup vs baseline: 1.0107x; 1.0107x over previous
.LBB0_315:
	v_lshlrev_b32_e32 v142, 4, v0
	s_lshl_b32 s100, s57, 14
	s_add_u32 s100, s18, s100
	s_addc_u32 s101, s19, 0
	v_readfirstlane_b32 s25, v142
	s_nop 3
	s_add_i32 m0, s25, 0x20400
	s_nop 0
	global_load_lds_dwordx4 v142, s[100:101]
	v_add_u32_e32 v142, 0x2000, v142
	s_add_i32 m0, s25, 0x22400
	s_nop 0
	global_load_lds_dwordx4 v142, s[100:101]
	s_ashr_i32 s25, s24, 31
	s_lshl_b64 s[26:27], s[24:25], 19
	s_add_u32 s26, s37, s26
	s_addc_u32 s27, s44, s27
	s_and_b64 s[34:35], s[38:39], exec
	s_cselect_b32 s25, s27, s29
	s_cselect_b32 s58, s26, s28
	s_ashr_i32 s23, s22, 31
	s_lshl_b64 s[34:35], s[22:23], 19
	s_add_u32 s42, s40, s34
	s_addc_u32 s43, s41, s35
	s_and_b64 s[34:35], s[38:39], exec
	s_cselect_b32 s23, s43, s31
	s_cselect_b32 s59, s42, s30
	s_add_u32 s28, s28, 0x40080
	s_addc_u32 s29, s29, 0
	s_add_u32 s60, s30, 0x100
	v_mov_b32_e32 v4, 0
	s_addc_u32 s61, s31, 0
	s_mov_b32 s62, -2
	v_mov_b32_e32 v5, v4
	v_mov_b32_e32 v6, v4
	v_mov_b32_e32 v7, v4
	v_mov_b32_e32 v12, v4
	v_mov_b32_e32 v13, v4
	v_mov_b32_e32 v14, v4
	v_mov_b32_e32 v15, v4
	v_mov_b32_e32 v20, v4
	v_mov_b32_e32 v21, v4
	v_mov_b32_e32 v22, v4
	v_mov_b32_e32 v23, v4
	v_mov_b32_e32 v28, v4
	v_mov_b32_e32 v29, v4
	v_mov_b32_e32 v30, v4
	v_mov_b32_e32 v31, v4
	v_mov_b32_e32 v36, v4
	v_mov_b32_e32 v37, v4
	v_mov_b32_e32 v38, v4
	v_mov_b32_e32 v39, v4
	v_mov_b32_e32 v44, v4
	v_mov_b32_e32 v45, v4
	v_mov_b32_e32 v46, v4
	v_mov_b32_e32 v47, v4
	v_mov_b32_e32 v52, v4
	v_mov_b32_e32 v53, v4
	v_mov_b32_e32 v54, v4
	v_mov_b32_e32 v55, v4
	v_mov_b32_e32 v60, v4
	v_mov_b32_e32 v61, v4
	v_mov_b32_e32 v62, v4
	v_mov_b32_e32 v63, v4
	v_mov_b32_e32 v8, v4
	v_mov_b32_e32 v9, v4
	v_mov_b32_e32 v10, v4
	v_mov_b32_e32 v11, v4
	v_mov_b32_e32 v16, v4
	v_mov_b32_e32 v17, v4
	v_mov_b32_e32 v18, v4
	v_mov_b32_e32 v19, v4
	v_mov_b32_e32 v24, v4
	v_mov_b32_e32 v25, v4
	v_mov_b32_e32 v26, v4
	v_mov_b32_e32 v27, v4
	v_mov_b32_e32 v32, v4
	v_mov_b32_e32 v33, v4
	v_mov_b32_e32 v34, v4
	v_mov_b32_e32 v35, v4
	v_mov_b32_e32 v40, v4
	v_mov_b32_e32 v41, v4
	v_mov_b32_e32 v42, v4
	v_mov_b32_e32 v43, v4
	v_mov_b32_e32 v48, v4
	v_mov_b32_e32 v49, v4
	v_mov_b32_e32 v50, v4
	v_mov_b32_e32 v51, v4
	v_mov_b32_e32 v56, v4
	v_mov_b32_e32 v57, v4
	v_mov_b32_e32 v58, v4
	v_mov_b32_e32 v59, v4
	v_mov_b32_e32 v64, v4
	v_mov_b32_e32 v65, v4
	v_mov_b32_e32 v66, v4
	v_mov_b32_e32 v67, v4
	v_mov_b32_e32 v68, v4
	v_mov_b32_e32 v69, v4
	v_mov_b32_e32 v70, v4
	v_mov_b32_e32 v71, v4
	v_mov_b32_e32 v76, v4
	v_mov_b32_e32 v77, v4
	v_mov_b32_e32 v78, v4
	v_mov_b32_e32 v79, v4
	v_mov_b32_e32 v84, v4
	v_mov_b32_e32 v85, v4
	v_mov_b32_e32 v86, v4
	v_mov_b32_e32 v87, v4
	v_mov_b32_e32 v92, v4
	v_mov_b32_e32 v93, v4
	v_mov_b32_e32 v94, v4
	v_mov_b32_e32 v95, v4
	v_mov_b32_e32 v100, v4
	v_mov_b32_e32 v101, v4
	v_mov_b32_e32 v102, v4
	v_mov_b32_e32 v103, v4
	v_mov_b32_e32 v108, v4
	v_mov_b32_e32 v109, v4
	v_mov_b32_e32 v110, v4
	v_mov_b32_e32 v111, v4
	v_mov_b32_e32 v116, v4
	v_mov_b32_e32 v117, v4
	v_mov_b32_e32 v118, v4
	v_mov_b32_e32 v119, v4
	v_mov_b32_e32 v124, v4
	v_mov_b32_e32 v125, v4
	v_mov_b32_e32 v126, v4
	v_mov_b32_e32 v127, v4
	v_mov_b32_e32 v72, v4
	v_mov_b32_e32 v73, v4
	v_mov_b32_e32 v74, v4
	v_mov_b32_e32 v75, v4
	v_mov_b32_e32 v80, v4
	v_mov_b32_e32 v81, v4
	v_mov_b32_e32 v82, v4
	v_mov_b32_e32 v83, v4
	v_mov_b32_e32 v88, v4
	v_mov_b32_e32 v89, v4
	v_mov_b32_e32 v90, v4
	v_mov_b32_e32 v91, v4
	v_mov_b32_e32 v96, v4
	v_mov_b32_e32 v97, v4
	v_mov_b32_e32 v98, v4
	v_mov_b32_e32 v99, v4
	v_mov_b32_e32 v104, v4
	v_mov_b32_e32 v105, v4
	v_mov_b32_e32 v106, v4
	v_mov_b32_e32 v107, v4
	v_mov_b32_e32 v112, v4
	v_mov_b32_e32 v113, v4
	v_mov_b32_e32 v114, v4
	v_mov_b32_e32 v115, v4
	v_mov_b32_e32 v120, v4
	v_mov_b32_e32 v121, v4
	v_mov_b32_e32 v122, v4
	v_mov_b32_e32 v123, v4
	v_mov_b32_e32 v128, v4
	v_mov_b32_e32 v129, v4
	v_mov_b32_e32 v130, v4
	v_mov_b32_e32 v131, v4

.LBB0_319:
	v_mov_b32_e32 v142, v1
	v_mov_b32_e32 v143, v144
	s_lshl_b32 s23, s57, 8
	v_lshl_add_u32 v143, v143, 4, v142
	v_add_u32_e32 v147, s53, v143
	v_cmp_gt_i32_e32 vcc, s85, v147
	s_and_saveexec_b64 s[28:29], vcc
	s_cbranch_execz .LBB0_321
	v_lshlrev_b32_e32 v160, 6, v147
	v_add_u32_e32 v160, 0x20400, v160
	ds_read_b128 v[148:151], v160
	ds_read_b128 v[152:155], v160 offset:32
	ds_read_b128 v[156:159], v160 offset:16
	ds_read_b128 v[160:163], v160 offset:48
	s_mov_b32 s25, 0x800000
	v_lshl_add_u32 v147, v147, 2, v225
	s_waitcnt lgkmcnt(0)
	v_mov_b32_e32 v164, v148
	v_mov_b32_e32 v165, v152
	v_mov_b32_e32 v152, v149
	v_mov_b32_e32 v148, v150
	v_mov_b32_e32 v149, v154
	v_mov_b32_e32 v154, v151
	v_mov_b32_e32 v150, v156
	v_mov_b32_e32 v151, v160
	v_mov_b32_e32 v160, v157
	v_mov_b32_e32 v156, v158
	v_mov_b32_e32 v157, v162
	v_mov_b32_e32 v162, v159
	v_pk_add_f32 v[152:153], v[164:165], v[152:153]
	v_pk_add_f32 v[148:149], v[148:149], v[154:155]
	v_pk_add_f32 v[150:151], v[150:151], v[160:161]
	v_pk_add_f32 v[154:155], v[156:157], v[162:163]
	v_pk_add_f32 v[148:149], v[152:153], v[148:149]
	v_pk_add_f32 v[150:151], v[150:151], v[154:155]
	s_nop 0
	v_pk_add_f32 v[148:149], v[148:149], v[150:151]
	s_nop 0
	v_add_f32_e32 v148, v148, v149
	v_fmamk_f32 v148, v148, 0x3a800000, v223
	v_mul_f32_e32 v149, 0x4b800000, v148
	v_cmp_gt_f32_e32 vcc, s25, v148
	s_nop 1
	v_cndmask_b32_e32 v148, v148, v149, vcc
	v_rsq_f32_e32 v148, v148
	s_nop 0
	v_mul_f32_e32 v149, 0x45800000, v148
	v_cndmask_b32_e32 v148, v148, v149, vcc
	ds_write_b32 v147, v148

	.amdhsa_kernel _Z7enc_fwd4Args
		.amdhsa_group_segment_fixed_size 0
		.amdhsa_private_segment_fixed_size 0
		.amdhsa_kernarg_size 480
		.amdhsa_user_sgpr_count 2
		.amdhsa_user_sgpr_dispatch_ptr 0
		.amdhsa_user_sgpr_queue_ptr 0
		.amdhsa_user_sgpr_kernarg_segment_ptr 1
		.amdhsa_user_sgpr_dispatch_id 0
		.amdhsa_user_sgpr_kernarg_preload_length 0
		.amdhsa_user_sgpr_kernarg_preload_offset 0
		.amdhsa_user_sgpr_private_segment_size 0
		.amdhsa_uses_dynamic_stack 0
		.amdhsa_enable_private_segment 0
		.amdhsa_system_sgpr_workgroup_id_x 1
		.amdhsa_system_sgpr_workgroup_id_y 0
		.amdhsa_system_sgpr_workgroup_id_z 0
		.amdhsa_system_sgpr_workgroup_info 0
		.amdhsa_system_vgpr_workitem_id 0
		.amdhsa_next_free_vgpr 256
		.amdhsa_next_free_sgpr 102
		.amdhsa_accum_offset 256
		.amdhsa_reserve_vcc 1
		.amdhsa_float_round_mode_32 0
		.amdhsa_float_round_mode_16_64 0
		.amdhsa_float_denorm_mode_32 3
		.amdhsa_float_denorm_mode_16_64 3
		.amdhsa_dx10_clamp 1
		.amdhsa_ieee_mode 1
		.amdhsa_fp16_overflow 0
		.amdhsa_tg_split 0
		.amdhsa_exception_fp_ieee_invalid_op 0
		.amdhsa_exception_fp_denorm_src 0
		.amdhsa_exception_fp_ieee_div_zero 0
		.amdhsa_exception_fp_ieee_overflow 0
		.amdhsa_exception_fp_ieee_underflow 0
		.amdhsa_exception_fp_ieee_inexact 0
		.amdhsa_exception_int_div_zero 0
	.end_amdhsa_kernel
